# cooperative-groups grid.sync after phase 0 replaced by a copy of the XCD-hierarchical barrier
# speedup vs baseline: 1.0051x; 1.0051x over previous
; DI unsigned xb_ld(unsigned* p) { return __hip_atomic_load(p, __ATOMIC_RELAXED, __HIP_MEMORY_SCOPE_AGENT); }
; DI unsigned xb_add(unsigned* p, unsigned v) { return __hip_atomic_fetch_add(p, v, __ATOMIC_RELAXED, __HIP_MEMORY_SCOPE_AGENT); }
; DI void xcd_barrier_complete(unsigned* bar, unsigned x, unsigned& nloc, unsigned& nx) {
;   const unsigned G = gridDim.x;
;   unsigned sum, cnt, mine;
;   for (;;) {
;     sum = 0u; cnt = 0u; mine = 0u;
; #pragma unroll
;     for (unsigned j = 0; j < 16; ++j) { const unsigned c = xb_ld(&bar[XB_XCNT(j)]); sum += c; cnt += (c > 0u) ? 1u : 0u; mine = (j == x) ? c : mine; }
;     if (sum == G) break;
; DI void xcd_barrier(const XcdBarrier& b) {
;   asm volatile("s_waitcnt vmcnt(0)" ::: "memory");
;   __syncthreads();
;   if (threadIdx.x == 0) {
;     unsigned* bar = b.bar;
;     unsigned bx = b.x;
;     asm volatile("" : "+s"(bx));
;     __builtin_amdgcn_s_waitcnt(0);
;     unsigned nloc = b.st[0], nx = b.st[1];
;     if (nloc == 0u) { xcd_barrier_complete(bar, bx, nloc, nx); b.st[0] = nloc; b.st[1] = nx; }
;     const unsigned old = xb_add(&bar[XB_XSUB(bx)], 1u);
.LBB0_75:
	s_waitcnt vmcnt(0)
	s_barrier
	s_and_saveexec_b64 s[0:1], s[68:69]
	s_cbranch_execz .Lgs_end
	s_add_i32 s2, 16, 0x20000
	v_readlane_b32 s33, v252, 18
	v_mov_b32_e32 v0, s2
	s_waitcnt vmcnt(0) expcnt(0) lgkmcnt(0)
	ds_read_b32 v1, v0
	s_add_i32 s2, 16, 0x20004
	v_mov_b32_e32 v0, s2
	ds_read_b32 v0, v0
	s_waitcnt lgkmcnt(1)
	v_cmp_ne_u32_e32 vcc, 0, v1
	s_cbranch_vccnz .Lgs_95
	s_add_u32 s2, s58, 0x1400
	s_addc_u32 s3, s59, 0
	s_add_u32 s4, s58, 0x1500
	s_addc_u32 s5, s59, 0
	s_add_u32 s6, s58, 0x1600
	s_addc_u32 s7, s59, 0
	s_add_u32 s8, s58, 0x1700
	s_addc_u32 s9, s59, 0
	s_add_u32 s10, s58, 0x1800
	s_addc_u32 s11, s59, 0
	s_add_u32 s12, s58, 0x1900
	s_addc_u32 s13, s59, 0
	s_add_u32 s14, s58, 0x1a00
	s_addc_u32 s15, s59, 0
	s_add_u32 s16, s58, 0x1b00
	s_addc_u32 s17, s59, 0
	s_add_u32 s18, s58, 0x1c00
	s_addc_u32 s19, s59, 0
	s_add_u32 s20, s58, 0x1d00
	s_addc_u32 s21, s59, 0
	s_add_u32 s22, s58, 0x1e00
	s_addc_u32 s23, s59, 0
	s_add_u32 s24, s58, 0x1f00
	s_addc_u32 s25, s59, 0
	s_add_u32 s26, s58, 0x2000
	s_addc_u32 s27, s59, 0
	s_add_u32 s28, s58, 0x2100
	s_addc_u32 s29, s59, 0
	s_add_u32 s30, s58, 0x2200
	s_addc_u32 s31, s59, 0
	s_add_u32 s34, s58, 0x2300
	s_addc_u32 s35, s59, 0
	v_mov_b32_e32 v16, 0
	s_branch .Lgs_92

; DI unsigned xb_ld(unsigned* p) { return __hip_atomic_load(p, __ATOMIC_RELAXED, __HIP_MEMORY_SCOPE_AGENT); }
; DI unsigned xb_add(unsigned* p, unsigned v) { return __hip_atomic_fetch_add(p, v, __ATOMIC_RELAXED, __HIP_MEMORY_SCOPE_AGENT); }
; DI void xcd_barrier(const XcdBarrier& b) {
;     ...
;   if (threadIdx.x == 0) {
;     unsigned* bar = b.bar;
;     unsigned bx = b.x;
;     asm volatile("" : "+s"(bx));
;     __builtin_amdgcn_s_waitcnt(0);
;     unsigned nloc = b.st[0], nx = b.st[1];
;     if (nloc == 0u) { xcd_barrier_complete(bar, bx, nloc, nx); b.st[0] = nloc; b.st[1] = nx; }
;     const unsigned old = xb_add(&bar[XB_XSUB(bx)], 1u);
;     const unsigned gen = old / nloc;
;     if (old + 1u == (gen + 1u) * nloc) {
;       __builtin_amdgcn_fence(__ATOMIC_RELEASE, "agent");
;       asm volatile("s_waitcnt vmcnt(0)" ::: "memory");
;       const unsigned og = xb_add(&bar[XB_TOP], 1u);
;       const unsigned tg = og / nx;
;       if (og + 1u == (tg + 1u) * nx) xb_add(&bar[XB_TOPGEN], 1u);
;       else { while (xb_ld(&bar[XB_TOPGEN]) == tg) __builtin_amdgcn_s_sleep(1); }
;       __builtin_amdgcn_fence(__ATOMIC_ACQUIRE, "agent");
;       xb_add(&bar[XB_XGEN(bx)], 1u);
;       asm volatile("s_waitcnt vmcnt(0)" ::: "memory");
;     } else {
;       while (xb_ld(&bar[XB_XGEN(bx)]) == gen) __builtin_amdgcn_s_sleep(1);
;       __builtin_amdgcn_fence(__ATOMIC_ACQUIRE, "agent");
;       asm volatile("s_waitcnt vmcnt(0)" ::: "memory");
;     }
;   }
;   __syncthreads();
.Lgs_end:
	s_or_b64 exec, exec, s[0:1]
	v_readlane_b32 s12, v252, 19
	v_readlane_b32 s13, v252, 20
	v_readlane_b32 s14, v252, 21
	v_readlane_b32 s15, v252, 22
	v_readlane_b32 s16, v252, 23
	v_readlane_b32 s17, v252, 24
	v_readlane_b32 s18, v252, 25
	v_readlane_b32 s19, v252, 26
	v_readlane_b32 s20, v252, 27
	v_readlane_b32 s21, v252, 28
	v_readlane_b32 s22, v252, 29
	v_readlane_b32 s23, v252, 30
	v_readlane_b32 s24, v252, 31
	v_readlane_b32 s25, v252, 32
	v_readlane_b32 s26, v252, 33
	v_readlane_b32 s27, v252, 34
	s_mov_b64 s[0:1], exec
